# LDS-DMA issue moved to between QK and PV phases in differential-attention loops too
# speedup vs baseline: 1.1080x; 1.0140x over previous
; __device__ __forceinline__ void finishSM(f32x16& p0, f32x16& p1, float alpha, float& l_reg, bf16x8& pa0, bf16x8& pa1, bf16x8& pa2, bf16x8& pa3) {
; #pragma unroll
;   for (int r = 0; r < 16; ++r) p1[r] = __builtin_amdgcn_exp2f(p1[r]);
;   float ps = 0;
; #pragma unroll
;   for (int r = 0; r < 16; ++r) ps += p0[r];
; #pragma unroll
;   for (int r = 0; r < 16; ++r) ps += p1[r];
;   { auto rr = __builtin_amdgcn_permlane32_swap(__float_as_uint(ps), __float_as_uint(ps), false, false);
;     ps = __uint_as_float(rr[0]) + __uint_as_float(rr[1]); }
;   l_reg = l_reg * alpha + ps;
;     ...
;   PK4(p0, 0, pa0); PK4(p0, 8, pa1); PK4(p1, 0, pa2); PK4(p1, 8, pa3);
;     ...
; }
; template <int ND0, int DOFF>
; __device__ __forceinline__ void qkt(f32x16& p0, f32x16& p1, const char* Ks, const bf16x8* qr, int r32, int hi) {
;   p0 = f32x16{}; p1 = f32x16{};
; #pragma unroll
;   for (int d0 = 0; d0 < ND0; ++d0) { const int cb = ((d0 + DOFF) * 16 + hi * 8) * 2;
;     bf16x8 b0 = *reinterpret_cast<const bf16x8*>(Ks + KSWZ(r32, cb));
;     bf16x8 b1 = *reinterpret_cast<const bf16x8*>(Ks + KSWZ(32 + r32, cb));
;     p0 = __builtin_amdgcn_mfma_f32_32x32x16_bf16(b0, qr[d0], p0, 0, 0, 0);
;     p1 = __builtin_amdgcn_mfma_f32_32x32x16_bf16(b1, qr[d0], p1, 0, 0, 0); }
; }
; __device__ __forceinline__ int v_st(int k, int c) { const int kk = (k & ~0xC) | ((k & 4) << 1) | ((k & 8) >> 1); return ((kk >> 3) * 4 + (c >> 5)) * 512 + ((kk & 7) * 32 + (c & 31)) * 2; }
; __device__ __forceinline__ int v_rd_base(int lane) { return ((lane & 3) << 3) | (((lane >> 2) & 3) << 6) | (((lane >> 4) & 1) << 5) | (((lane >> 5) & 1) << 8); }
; template <int OFF> __device__ __forceinline__ s16x4 tr_read(int vb) {
;   s16x4 r; asm volatile("ds_read_b64_tr_b16 %0, %1 offset:%2" : "=&v"(r) : "v"(vb), "i"(OFF) : "memory"); return r;
; }
; template <int MODE>
; __device__ __forceinline__ void attn_body(const bf16_t* __restrict__ Qb, const bf16_t* __restrict__ Kh, const bf16_t* __restrict__ Vh, int NT, int krel0,
;                                           char* lds, const float* __restrict__ lutg, const AttnEpi& E) {
;     ...
;   for (int j = 1; j + 1 < NT; j += 2) {
;     __syncthreads();
;     SBAR(); qkt<ND0, DOFF>(pB0, pB1, K_lds + oq, qr, r32, hi);
;     finishSM(pA0, pA1, alA, l_reg, pa0, pa1, pa2, pa3); SBAR();
;     SLOAD(SO, (j + 2) * 64); SBAR();
;     pv_d0(o, vb0 + op, pa0, pa1, pa2, pa3); PSM(pB0, pB1, mnB, alB, j);
.LBB0_132:
	v_readfirstlane_b32 s20, v221
	v_readfirstlane_b32 s21, v220
	s_nop 3
	s_add_i32 s22, s20, s77
	s_addk_i32 s22, 0x7f
	s_add_i32 s23, s21, s77
	s_addk_i32 s23, 0x40
	s_add_i32 s24, s22, 64
	s_add_i32 s25, s23, 64
	s_mov_b32 s79, s64
	s_waitcnt vmcnt(0) lgkmcnt(0)
	s_barrier
	s_add_i32 s64, s82, 0
	v_add_u32_e32 v0, s64, v213
	ds_read_b128 v[98:101], v0 offset:49152
	ds_read_b128 v[102:105], v0 offset:57344
	v_add_u32_e32 v0, s64, v214
	ds_read_b128 v[162:165], v0 offset:49152
	ds_read_b128 v[166:169], v0 offset:57344
	v_add_u32_e32 v0, s64, v215
	s_waitcnt lgkmcnt(3)
	v_mfma_f32_32x32x16_bf16 v[114:129], v[98:101], v[142:145], 0
	s_waitcnt lgkmcnt(2)
	v_mfma_f32_32x32x16_bf16 v[98:113], v[102:105], v[142:145], 0
	s_waitcnt lgkmcnt(1)
	v_mfma_f32_32x32x16_bf16 v[114:129], v[162:165], v[138:141], v[114:129]
	s_waitcnt lgkmcnt(0)
	v_mfma_f32_32x32x16_bf16 v[98:113], v[166:169], v[138:141], v[98:113]
	ds_read_b128 v[162:165], v0 offset:49152
	ds_read_b128 v[166:169], v0 offset:57344
	v_add_u32_e32 v0, s64, v216
	s_waitcnt lgkmcnt(1)
	v_mfma_f32_32x32x16_bf16 v[114:129], v[162:165], v[134:137], v[114:129]
	s_waitcnt lgkmcnt(0)
	v_mfma_f32_32x32x16_bf16 v[98:113], v[166:169], v[134:137], v[98:113]
	ds_read_b128 v[162:165], v0 offset:49152
	ds_read_b128 v[166:169], v0 offset:57344
	v_exp_f32_e32 v0, v82
	v_exp_f32_e32 v82, v83
	v_exp_f32_e32 v83, v84
	v_exp_f32_e32 v84, v85
	v_exp_f32_e32 v85, v86
	v_exp_f32_e32 v86, v87
	v_exp_f32_e32 v87, v88
	v_exp_f32_e32 v88, v89
	v_exp_f32_e32 v89, v90
	v_exp_f32_e32 v90, v91
	v_exp_f32_e32 v91, v92
	v_exp_f32_e32 v92, v93
	v_exp_f32_e32 v93, v94
	v_exp_f32_e32 v94, v95
	v_exp_f32_e32 v95, v96
	v_exp_f32_e32 v96, v97
	v_add_f32_e32 v97, v67, v66
	v_add_f32_e32 v97, v68, v97
	v_add_f32_e32 v97, v69, v97
	v_add_f32_e32 v97, v70, v97
	v_add_f32_e32 v97, v71, v97
	v_add_f32_e32 v97, v72, v97
	v_add_f32_e32 v97, v73, v97
	v_add_f32_e32 v97, v74, v97
	v_add_f32_e32 v97, v75, v97
	v_add_f32_e32 v97, v76, v97
	v_add_f32_e32 v97, v77, v97
	v_add_f32_e32 v97, v78, v97
	v_add_f32_e32 v97, v79, v97
	v_add_f32_e32 v97, v80, v97
	v_add_f32_e32 v97, v81, v97
	v_add_f32_e32 v97, v0, v97
	v_add_f32_e32 v97, v82, v97
	v_add_f32_e32 v97, v83, v97
	v_add_f32_e32 v97, v84, v97
	v_add_f32_e32 v97, v85, v97
	v_add_f32_e32 v97, v86, v97
	v_add_f32_e32 v97, v87, v97
	v_add_f32_e32 v97, v88, v97
	v_add_f32_e32 v97, v89, v97
	v_add_f32_e32 v97, v90, v97
	s_waitcnt lgkmcnt(1)
	v_mfma_f32_32x32x16_bf16 v[114:129], v[162:165], v[130:133], v[114:129]
	v_add_f32_e32 v97, v91, v97
	v_add_f32_e32 v97, v92, v97
	v_add_f32_e32 v97, v93, v97
	v_add_f32_e32 v97, v94, v97
	v_add_f32_e32 v97, v95, v97
	v_add_f32_e32 v223, v96, v97
	v_mov_b32_e32 v224, v223
	s_waitcnt lgkmcnt(0)
	v_mfma_f32_32x32x16_bf16 v[98:113], v[166:169], v[130:133], v[98:113]
	v_cvt_pk_bf16_f32 v66, v66, v67
	v_cvt_pk_bf16_f32 v67, v68, v69
	v_cvt_pk_bf16_f32 v68, v70, v71
	v_cvt_pk_bf16_f32 v69, v72, v73
	v_cvt_pk_bf16_f32 v70, v74, v75
	v_cvt_pk_bf16_f32 v71, v76, v77
	v_cvt_pk_bf16_f32 v72, v78, v79
	v_cvt_pk_bf16_f32 v73, v80, v81
	v_cvt_pk_bf16_f32 v74, v0, v82
	v_cvt_pk_bf16_f32 v75, v83, v84
	v_cvt_pk_bf16_f32 v76, v85, v86
	v_cvt_pk_bf16_f32 v77, v87, v88
	v_cvt_pk_bf16_f32 v78, v89, v90
	v_cvt_pk_bf16_f32 v79, v91, v92
	v_cvt_pk_bf16_f32 v80, v93, v94
	v_cvt_pk_bf16_f32 v81, v95, v96
	v_permlane32_swap_b32_e32 v223, v224
	v_permlane32_swap_b32_e32 v66, v68
	v_permlane32_swap_b32_e32 v67, v69
	v_permlane32_swap_b32_e32 v70, v72
	v_permlane32_swap_b32_e32 v71, v73
	v_permlane32_swap_b32_e32 v74, v76
	v_permlane32_swap_b32_e32 v75, v77
	v_permlane32_swap_b32_e32 v78, v80
	v_permlane32_swap_b32_e32 v79, v81
	s_add_i32 m0, s79, s30
	s_nop 0
	global_load_lds_dwordx4 v248, s[26:27]
	s_add_i32 m0, m0, 0x400
	s_nop 0
	global_load_lds_dwordx4 v249, s[26:27]
	s_add_i32 m0, m0, 0xbc00
	s_nop 0
	global_load_lds_dwordx4 v250, s[28:29]
	s_add_i32 m0, m0, 0x400
	s_nop 0
	global_load_lds_dwordx4 v251, s[28:29]
	s_add_u32 s26, s26, 0x90000
	s_addc_u32 s27, s27, 0
	s_add_u32 s28, s28, 0x90000
	s_addc_u32 s29, s29, 0
	v_add_u32_e32 v0, s80, v218
	ds_read_b64_tr_b16 v[82:83], v0 offset:0
	ds_read_b64_tr_b16 v[84:85], v0 offset:0x800
	ds_read_b64_tr_b16 v[86:87], v0 offset:0x1000
	ds_read_b64_tr_b16 v[88:89], v0 offset:0x1800
	ds_read_b64_tr_b16 v[90:91], v0 offset:0x2000
	ds_read_b64_tr_b16 v[92:93], v0 offset:0x2800
	ds_read_b64_tr_b16 v[94:95], v0 offset:0x3000
	ds_read_b64_tr_b16 v[96:97], v0 offset:0x3800
	s_waitcnt lgkmcnt(0)
	s_nop 0
	v_mfma_f32_32x32x16_bf16 v[50:65], v[66:69], v[82:85], v[50:65]
	ds_read_b64_tr_b16 v[82:83], v0 offset:0x200
	ds_read_b64_tr_b16 v[84:85], v0 offset:0xa00
	v_mfma_f32_32x32x16_bf16 v[50:65], v[70:73], v[86:89], v[50:65]
	ds_read_b64_tr_b16 v[86:87], v0 offset:0x1200
	ds_read_b64_tr_b16 v[88:89], v0 offset:0x1a00
	v_mfma_f32_32x32x16_bf16 v[50:65], v[74:77], v[90:93], v[50:65]
	ds_read_b64_tr_b16 v[90:91], v0 offset:0x2200
	ds_read_b64_tr_b16 v[92:93], v0 offset:0x2a00
	v_mfma_f32_32x32x16_bf16 v[50:65], v[78:81], v[94:97], v[50:65]
	ds_read_b64_tr_b16 v[94:95], v0 offset:0x3200
	ds_read_b64_tr_b16 v[96:97], v0 offset:0x3a00
	s_waitcnt lgkmcnt(0)
	v_mfma_f32_32x32x16_bf16 v[34:49], v[66:69], v[82:85], v[34:49]
	ds_read_b64_tr_b16 v[82:83], v0 offset:0x400
	ds_read_b64_tr_b16 v[84:85], v0 offset:0xc00
	v_mfma_f32_32x32x16_bf16 v[34:49], v[70:73], v[86:89], v[34:49]
	ds_read_b64_tr_b16 v[86:87], v0 offset:0x1400
	ds_read_b64_tr_b16 v[88:89], v0 offset:0x1c00
	v_mfma_f32_32x32x16_bf16 v[34:49], v[74:77], v[90:93], v[34:49]
	ds_read_b64_tr_b16 v[90:91], v0 offset:0x2400
	ds_read_b64_tr_b16 v[92:93], v0 offset:0x2c00
	v_mfma_f32_32x32x16_bf16 v[34:49], v[78:81], v[94:97], v[34:49]
	ds_read_b64_tr_b16 v[94:95], v0 offset:0x3400
	ds_read_b64_tr_b16 v[96:97], v0 offset:0x3c00
	s_waitcnt lgkmcnt(0)
	v_mfma_f32_32x32x16_bf16 v[18:33], v[66:69], v[82:85], v[18:33]
	ds_read_b64_tr_b16 v[82:83], v0 offset:0x600
	ds_read_b64_tr_b16 v[84:85], v0 offset:0xe00
	v_mfma_f32_32x32x16_bf16 v[18:33], v[70:73], v[86:89], v[18:33]
	ds_read_b64_tr_b16 v[86:87], v0 offset:0x1600
	ds_read_b64_tr_b16 v[88:89], v0 offset:0x1e00
	v_mfma_f32_32x32x16_bf16 v[18:33], v[74:77], v[90:93], v[18:33]
	ds_read_b64_tr_b16 v[90:91], v0 offset:0x2600
	ds_read_b64_tr_b16 v[92:93], v0 offset:0x2e00
	v_mfma_f32_32x32x16_bf16 v[18:33], v[78:81], v[94:97], v[18:33]
	ds_read_b64_tr_b16 v[94:95], v0 offset:0x3600
	ds_read_b64_tr_b16 v[96:97], v0 offset:0x3e00
	s_waitcnt lgkmcnt(0)
	v_mfma_f32_32x32x16_bf16 v[2:17], v[66:69], v[82:85], v[2:17]
	s_cmp_gt_i32 s95, s22
	s_cselect_b64 s[64:65], -1, 0
	s_cmp_lt_i32 s15, s22
	s_cselect_b64 vcc, -1, 0
	v_mov_b32_e32 v229, s76
	v_mfma_f32_32x32x16_bf16 v[2:17], v[70:73], v[86:89], v[2:17]
	v_mfma_f32_32x32x16_bf16 v[2:17], v[74:77], v[90:93], v[2:17]
	v_mfma_f32_32x32x16_bf16 v[2:17], v[78:81], v[94:97], v[2:17]
	s_and_saveexec_b64 s[66:67], vcc
	s_cbranch_execz .LBB0_136
; template <int MODE>
; __device__ __forceinline__ void partialSM(f32x16& p0, f32x16& p1, float& m_reg, float& mn, float& alpha, int relh, int relw_min, int relw_max, const float* lut) {
;     ...
;     if (nearT) {
; #pragma unroll
;       for (int r = 0; r < 16; ++r) { const int i0 = relh + (r & 3) + 8 * (r >> 2);
;         const int a0 = min(max(i0, -129), 129) + 129, a1 = min(max(i0 + 32, -129), 129) + 129;
;         p0[r] = fmaf(p0[r], C, lut[a0]); p1[r] = fmaf(p1[r], C, lut[a1]); }
	s_cmp_gt_i32 s91, s23
	s_cselect_b64 vcc, -1, 0
	s_mov_b64 s[70:71], -1
	s_and_saveexec_b64 s[68:69], vcc
	s_cbranch_execz .LBB0_135
	v_add_u32_e32 v227, s77, v222
	v_add_u32_e32 v66, 64, v227
	v_add_u32_e32 v68, 0x41, v227
	v_add_u32_e32 v70, 0x42, v227
	v_add_u32_e32 v72, 0x43, v227
	v_med3_i32 v67, v66, s39, v198
	v_med3_i32 v66, v66, s33, v199
	v_med3_i32 v69, v68, s39, v198
	v_med3_i32 v68, v68, s33, v199
	v_med3_i32 v71, v70, s39, v198
	v_med3_i32 v70, v70, s33, v199
	v_med3_i32 v73, v72, s39, v198
	v_med3_i32 v72, v72, s33, v199
	v_lshl_add_u32 v67, v67, 2, s76
	v_lshl_add_u32 v66, v66, 2, s76
	v_lshl_add_u32 v69, v69, 2, s76
	v_lshl_add_u32 v68, v68, 2, s76
	v_lshl_add_u32 v70, v70, 2, s76
	v_lshl_add_u32 v72, v72, 2, s76
	v_lshl_add_u32 v71, v71, 2, s76
	v_lshl_add_u32 v73, v73, 2, s76
	ds_read_b32 v194, v67 offset:516
	ds_read_b32 v66, v66 offset:644
	ds_read_b32 v195, v69 offset:516
	ds_read_b32 v67, v68 offset:644
	ds_read_b32 v229, v71 offset:516
	ds_read_b32 v68, v70 offset:644
	ds_read_b32 v230, v73 offset:516
	ds_read_b32 v69, v72 offset:644
	v_add_u32_e32 v70, 0x48, v227
	v_add_u32_e32 v72, 0x49, v227
	v_add_u32_e32 v74, 0x4a, v227
	v_add_u32_e32 v76, 0x4b, v227
	v_med3_i32 v71, v70, s39, v198
	v_med3_i32 v70, v70, s33, v199
	v_med3_i32 v73, v72, s39, v198
	v_med3_i32 v72, v72, s33, v199
	v_med3_i32 v75, v74, s39, v198
	v_med3_i32 v74, v74, s33, v199
	v_med3_i32 v77, v76, s39, v198
	v_med3_i32 v76, v76, s33, v199
	v_lshl_add_u32 v71, v71, 2, s76
	v_lshl_add_u32 v70, v70, 2, s76
	v_lshl_add_u32 v73, v73, 2, s76
	v_lshl_add_u32 v72, v72, 2, s76
	v_lshl_add_u32 v74, v74, 2, s76
	v_lshl_add_u32 v76, v76, 2, s76
	v_lshl_add_u32 v75, v75, 2, s76
	v_lshl_add_u32 v77, v77, 2, s76
	ds_read_b32 v231, v71 offset:516
	ds_read_b32 v70, v70 offset:644
	ds_read_b32 v232, v73 offset:516
	ds_read_b32 v71, v72 offset:644
	ds_read_b32 v233, v75 offset:516
	ds_read_b32 v72, v74 offset:644
	ds_read_b32 v234, v77 offset:516
	ds_read_b32 v73, v76 offset:644
	v_add_u32_e32 v74, 0x50, v227
	v_add_u32_e32 v76, 0x51, v227
	v_add_u32_e32 v78, 0x52, v227
	v_add_u32_e32 v80, 0x53, v227
	v_med3_i32 v75, v74, s39, v198
	v_med3_i32 v74, v74, s33, v199
	v_med3_i32 v77, v76, s39, v198
	v_med3_i32 v76, v76, s33, v199
	v_med3_i32 v79, v78, s39, v198
	v_med3_i32 v78, v78, s33, v199
	v_med3_i32 v81, v80, s39, v198
	v_med3_i32 v80, v80, s33, v199
	v_lshl_add_u32 v75, v75, 2, s76
	v_lshl_add_u32 v74, v74, 2, s76
	v_lshl_add_u32 v77, v77, 2, s76
	v_lshl_add_u32 v76, v76, 2, s76
	v_lshl_add_u32 v78, v78, 2, s76
	v_lshl_add_u32 v80, v80, 2, s76
	v_lshl_add_u32 v79, v79, 2, s76
	v_lshl_add_u32 v81, v81, 2, s76
	ds_read_b32 v235, v75 offset:516
	ds_read_b32 v74, v74 offset:644
	ds_read_b32 v236, v77 offset:516
	ds_read_b32 v75, v76 offset:644
	ds_read_b32 v237, v79 offset:516
	ds_read_b32 v76, v78 offset:644
	ds_read_b32 v238, v81 offset:516
	ds_read_b32 v77, v80 offset:644
	v_add_u32_e32 v78, 0x58, v227
	v_add_u32_e32 v80, 0x59, v227
	v_add_u32_e32 v82, 0x5a, v227
	v_med3_i32 v79, v78, s39, v198
	v_med3_i32 v78, v78, s33, v199
	v_med3_i32 v81, v80, s39, v198
	v_med3_i32 v80, v80, s33, v199
	v_med3_i32 v83, v82, s39, v198
	v_med3_i32 v82, v82, s33, v199
	v_add_u32_e32 v84, 0x5b, v227
	s_waitcnt lgkmcnt(14)
	v_fmac_f32_e32 v194, 0x3e38aa3b, v114
	v_fmac_f32_e32 v195, 0x3e38aa3b, v115
	v_lshl_add_u32 v79, v79, 2, s76
	v_lshl_add_u32 v78, v78, 2, s76
	v_lshl_add_u32 v81, v81, 2, s76
	v_lshl_add_u32 v80, v80, 2, s76
	v_lshl_add_u32 v82, v82, 2, s76
	v_med3_i32 v85, v84, s39, v198
	v_med3_i32 v84, v84, s33, v199
	v_fmac_f32_e32 v229, 0x3e38aa3b, v116
	v_fmac_f32_e32 v230, 0x3e38aa3b, v117
	v_lshl_add_u32 v83, v83, 2, s76
	v_lshl_add_u32 v85, v85, 2, s76
	v_lshl_add_u32 v84, v84, 2, s76
	ds_read_b32 v239, v79 offset:516
	ds_read_b32 v78, v78 offset:644
	ds_read_b32 v240, v81 offset:516
	ds_read_b32 v79, v80 offset:644
	ds_read_b32 v241, v83 offset:516
	ds_read_b32 v80, v82 offset:644
	ds_read_b32 v242, v85 offset:516
	ds_read_b32 v81, v84 offset:644
	v_max_f32_e32 v82, v194, v195
	v_fmac_f32_e32 v231, 0x3e38aa3b, v118
	s_waitcnt lgkmcnt(14)
; template <int MODE>
; __device__ __forceinline__ void partialSM(f32x16& p0, f32x16& p1, float& m_reg, float& mn, float& alpha, int relh, int relw_min, int relw_max, const float* lut) {
;     ...
;     float pmax = p0[0];
; #pragma unroll
;     for (int r = 1; r < 16; ++r) pmax = fmaxf(pmax, p0[r]);
; #pragma unroll
;     for (int r = 0; r < 16; ++r) pmax = fmaxf(pmax, p1[r]);
;     { auto rr = __builtin_amdgcn_permlane32_swap(__float_as_uint(pmax), __float_as_uint(pmax), false, false);
;       pmax = fmaxf(__uint_as_float(rr[0]), __uint_as_float(rr[1])); }
;     if (__builtin_expect(__all(pmax - m_reg <= THR2), 1)) { mn = m_reg; alpha = 1.f; }
;     else { mn = fmaxf(m_reg, pmax); alpha = __builtin_amdgcn_exp2f(m_reg - mn); m_reg = mn; }
; #pragma unroll
;     for (int r = 0; r < 16; ++r) p0[r] = __builtin_amdgcn_exp2f(p0[r] - mn);
; #pragma unroll
;     for (int r = 0; r < 16; ++r) p1[r] = p1[r] - mn;
	v_fmac_f32_e32 v232, 0x3e38aa3b, v119
	v_max3_f32 v82, v82, v229, v230
	v_fmac_f32_e32 v233, 0x3e38aa3b, v120
	v_fmac_f32_e32 v234, 0x3e38aa3b, v121
	v_max3_f32 v82, v82, v231, v232
	v_fmac_f32_e32 v235, 0x3e38aa3b, v122
	s_waitcnt lgkmcnt(13)
	v_fmac_f32_e32 v236, 0x3e38aa3b, v123
	v_max3_f32 v82, v82, v233, v234
	s_waitcnt lgkmcnt(11)
	v_fmac_f32_e32 v237, 0x3e38aa3b, v124
	s_waitcnt lgkmcnt(9)
	v_fmac_f32_e32 v238, 0x3e38aa3b, v125
	v_max3_f32 v82, v82, v235, v236
	s_waitcnt lgkmcnt(7)
	v_fmac_f32_e32 v239, 0x3e38aa3b, v126
	s_waitcnt lgkmcnt(5)
	v_fmac_f32_e32 v240, 0x3e38aa3b, v127
	v_max3_f32 v82, v82, v237, v238
	s_waitcnt lgkmcnt(3)
	v_fmac_f32_e32 v241, 0x3e38aa3b, v128
	s_waitcnt lgkmcnt(1)
	v_fmac_f32_e32 v242, 0x3e38aa3b, v129
	v_max3_f32 v82, v82, v239, v240
	v_max3_f32 v84, v82, v241, v242
	v_pk_fma_f32 v[82:83], v[98:99], s[48:49], v[66:67] op_sel_hi:[1,0,1]
	v_pk_fma_f32 v[86:87], v[102:103], s[48:49], v[70:71] op_sel_hi:[1,0,1]
	v_max3_f32 v66, v84, v82, v83
	v_pk_fma_f32 v[84:85], v[100:101], s[48:49], v[68:69] op_sel_hi:[1,0,1]
	v_pk_fma_f32 v[88:89], v[104:105], s[48:49], v[72:73] op_sel_hi:[1,0,1]
	v_max3_f32 v66, v66, v84, v85
	v_max3_f32 v66, v66, v86, v87
	v_max3_f32 v66, v66, v88, v89
	v_pk_fma_f32 v[90:91], v[106:107], s[48:49], v[74:75] op_sel_hi:[1,0,1]
	v_pk_fma_f32 v[92:93], v[108:109], s[48:49], v[76:77] op_sel_hi:[1,0,1]
	v_max3_f32 v66, v66, v90, v91
	v_max3_f32 v66, v66, v92, v93
	v_pk_fma_f32 v[94:95], v[110:111], s[48:49], v[78:79] op_sel_hi:[1,0,1]
	s_waitcnt lgkmcnt(0)
	v_pk_fma_f32 v[96:97], v[112:113], s[48:49], v[80:81] op_sel_hi:[1,0,1]
	v_max3_f32 v66, v66, v94, v95
	v_max3_f32 v66, v66, v96, v97
	v_mov_b32_e32 v67, v66
	s_nop 1
	v_permlane32_swap_b32_e32 v66, v67
	v_max_f32_e32 v66, v66, v67
	v_sub_f32_e32 v67, v66, v219
	v_cmp_ge_f32_e32 vcc, s94, v67
	v_max_f32_e32 v66, v219, v66
	v_sub_f32_e32 v67, v219, v66
	v_exp_f32_e32 v67, v67
	s_cmp_eq_u64 vcc, exec
	s_cselect_b64 vcc, -1, 0
	v_cndmask_b32_e32 v228, v66, v219, vcc
	v_cndmask_b32_e64 v226, v67, 1.0, vcc
	v_sub_f32_e32 v66, v194, v228
	v_sub_f32_e32 v67, v195, v228
	v_sub_f32_e32 v68, v229, v228
	v_sub_f32_e32 v69, v230, v228
	v_sub_f32_e32 v70, v231, v228
	v_sub_f32_e32 v71, v232, v228
	v_sub_f32_e32 v72, v233, v228
	v_sub_f32_e32 v73, v234, v228
	v_sub_f32_e32 v74, v235, v228
	v_sub_f32_e32 v75, v236, v228
	v_sub_f32_e32 v76, v237, v228
	v_sub_f32_e32 v77, v238, v228
	v_sub_f32_e32 v78, v239, v228
	v_sub_f32_e32 v79, v240, v228
	v_sub_f32_e32 v80, v241, v228
	v_sub_f32_e32 v81, v242, v228
	v_exp_f32_e32 v66, v66
	v_exp_f32_e32 v67, v67
	v_exp_f32_e32 v68, v68
	v_exp_f32_e32 v69, v69
	v_exp_f32_e32 v70, v70
	v_exp_f32_e32 v71, v71
	v_exp_f32_e32 v72, v72
	v_exp_f32_e32 v73, v73
	v_exp_f32_e32 v74, v74
	v_exp_f32_e32 v75, v75
	v_exp_f32_e32 v76, v76
	v_exp_f32_e32 v77, v77
	v_exp_f32_e32 v78, v78
	v_exp_f32_e32 v79, v79
	v_exp_f32_e32 v80, v80
	v_exp_f32_e32 v81, v81
	v_sub_f32_e32 v97, v97, v228
	v_sub_f32_e32 v96, v96, v228
	v_sub_f32_e32 v95, v95, v228
	v_sub_f32_e32 v94, v94, v228
	v_sub_f32_e32 v93, v93, v228
	v_sub_f32_e32 v92, v92, v228
	v_sub_f32_e32 v91, v91, v228
	v_sub_f32_e32 v90, v90, v228
	v_sub_f32_e32 v89, v89, v228
	v_sub_f32_e32 v88, v88, v228
	v_sub_f32_e32 v87, v87, v228
	v_sub_f32_e32 v86, v86, v228
	v_sub_f32_e32 v85, v85, v228
	v_sub_f32_e32 v84, v84, v228
	v_sub_f32_e32 v83, v83, v228
	v_sub_f32_e32 v82, v82, v228
	s_xor_b64 s[70:71], exec, -1

; #define SBAR() __builtin_amdgcn_sched_barrier(0)
; #define SLOAD(i, k0) do { sr_[i].vs0 = *reinterpret_cast<const bf16x8*>(&Vh[(size_t)((k0) + sr) * LDQK + sc]); sr_[i].vs1 = *reinterpret_cast<const bf16x8*>(&Vh[(size_t)((k0) + 32 + sr) * LDQK + sc]); \
;     sr_[i].ks0 = *reinterpret_cast<const bf16x8*>(&Kh[(size_t)((k0) + sr) * LDQK + sc]); sr_[i].ks1 = *reinterpret_cast<const bf16x8*>(&Kh[(size_t)((k0) + 32 + sr) * LDQK + sc]); } while (0)
; __device__ __forceinline__ void finishSM(f32x16& p0, f32x16& p1, float alpha, float& l_reg, bf16x8& pa0, bf16x8& pa1, bf16x8& pa2, bf16x8& pa3) {
; #pragma unroll
;   for (int r = 0; r < 16; ++r) p1[r] = __builtin_amdgcn_exp2f(p1[r]);
;   float ps = 0;
; #pragma unroll
;   for (int r = 0; r < 16; ++r) ps += p0[r];
; #pragma unroll
;   for (int r = 0; r < 16; ++r) ps += p1[r];
;   { auto rr = __builtin_amdgcn_permlane32_swap(__float_as_uint(ps), __float_as_uint(ps), false, false);
;     ps = __uint_as_float(rr[0]) + __uint_as_float(rr[1]); }
;   l_reg = l_reg * alpha + ps;
;     ...
;   PK4(p0, 0, pa0); PK4(p0, 8, pa1); PK4(p1, 0, pa2); PK4(p1, 8, pa3);
;     ...
; }
; template <int ND0, int DOFF>
; __device__ __forceinline__ void qkt(f32x16& p0, f32x16& p1, const char* Ks, const bf16x8* qr, int r32, int hi) {
;   p0 = f32x16{}; p1 = f32x16{};
; #pragma unroll
;   for (int d0 = 0; d0 < ND0; ++d0) { const int cb = ((d0 + DOFF) * 16 + hi * 8) * 2;
;     bf16x8 b0 = *reinterpret_cast<const bf16x8*>(Ks + KSWZ(r32, cb));
;     bf16x8 b1 = *reinterpret_cast<const bf16x8*>(Ks + KSWZ(32 + r32, cb));
;     p0 = __builtin_amdgcn_mfma_f32_32x32x16_bf16(b0, qr[d0], p0, 0, 0, 0);
;     p1 = __builtin_amdgcn_mfma_f32_32x32x16_bf16(b1, qr[d0], p1, 0, 0, 0); }
; }
; template <int MODE>
; __device__ __forceinline__ void attn_body(const bf16_t* __restrict__ Qb, const bf16_t* __restrict__ Kh, const bf16_t* __restrict__ Vh, int NT, int krel0,
;                                           char* lds, const float* __restrict__ lutg, const AttnEpi& E) {
;     ...
;     __syncthreads();
;     SBAR(); qkt<ND0, DOFF>(pA0, pA1, K_lds + oq, qr, r32, hi);
;     finishSM(pB0, pB1, alB, l_reg, pa0, pa1, pa2, pa3); SBAR();
;     if (j + 3 < NT) SLOAD(SE, (j + 3) * 64); SBAR();
.LBB0_142:
	s_waitcnt vmcnt(0) lgkmcnt(0)
	s_barrier
	v_add_u32_e32 v102, s66, v213
	ds_read_b128 v[98:101], v102 offset:49152
	ds_read_b128 v[102:105], v102 offset:57344
	v_add_u32_e32 v194, s66, v214
	ds_read_b128 v[230:233], v194 offset:49152
	ds_read_b128 v[234:237], v194 offset:57344
	v_add_u32_e32 v194, s66, v215
	s_waitcnt lgkmcnt(3)
	v_mfma_f32_32x32x16_bf16 v[114:129], v[98:101], v[142:145], 0
	v_exp_f32_e32 v82, v82
	v_exp_f32_e32 v83, v83
	v_exp_f32_e32 v84, v84
	v_exp_f32_e32 v85, v85
	v_exp_f32_e32 v86, v86
	v_exp_f32_e32 v87, v87
	v_exp_f32_e32 v88, v88
	s_waitcnt lgkmcnt(2)
	v_mfma_f32_32x32x16_bf16 v[98:113], v[102:105], v[142:145], 0
	v_exp_f32_e32 v89, v89
	v_exp_f32_e32 v90, v90
	v_exp_f32_e32 v91, v91
	v_exp_f32_e32 v92, v92
	v_exp_f32_e32 v93, v93
	v_exp_f32_e32 v94, v94
	v_exp_f32_e32 v95, v95
	s_waitcnt lgkmcnt(1)
	v_mfma_f32_32x32x16_bf16 v[114:129], v[230:233], v[138:141], v[114:129]
	v_exp_f32_e32 v96, v96
	v_exp_f32_e32 v97, v97
	s_waitcnt lgkmcnt(0)
	v_mfma_f32_32x32x16_bf16 v[98:113], v[234:237], v[138:141], v[98:113]
	ds_read_b128 v[230:233], v194 offset:49152
	ds_read_b128 v[234:237], v194 offset:57344
	v_add_u32_e32 v194, s66, v216
	s_waitcnt lgkmcnt(1)
	v_mfma_f32_32x32x16_bf16 v[114:129], v[230:233], v[134:137], v[114:129]
	s_waitcnt lgkmcnt(0)
	v_mfma_f32_32x32x16_bf16 v[98:113], v[234:237], v[134:137], v[98:113]
	ds_read_b128 v[230:233], v194 offset:49152
	ds_read_b128 v[234:237], v194 offset:57344
	v_add_f32_e32 v194, v67, v66
	v_add_f32_e32 v194, v68, v194
	v_add_f32_e32 v194, v69, v194
	v_add_f32_e32 v194, v70, v194
	v_add_f32_e32 v194, v71, v194
	v_add_f32_e32 v194, v72, v194
	v_add_f32_e32 v194, v73, v194
	v_add_f32_e32 v194, v74, v194
	v_add_f32_e32 v194, v75, v194
	v_add_f32_e32 v194, v76, v194
	v_add_f32_e32 v194, v77, v194
	v_add_f32_e32 v194, v78, v194
	v_add_f32_e32 v194, v79, v194
	v_add_f32_e32 v194, v80, v194
	v_add_f32_e32 v194, v81, v194
	v_add_f32_e32 v194, v82, v194
	v_add_f32_e32 v194, v83, v194
	v_add_f32_e32 v194, v84, v194
	v_add_f32_e32 v194, v85, v194
	v_add_f32_e32 v194, v86, v194
	v_add_f32_e32 v194, v87, v194
	v_add_f32_e32 v194, v88, v194
	v_add_f32_e32 v194, v89, v194
	v_add_f32_e32 v194, v90, v194
	v_add_f32_e32 v194, v91, v194
	s_waitcnt lgkmcnt(1)
	v_mfma_f32_32x32x16_bf16 v[114:129], v[230:233], v[130:133], v[114:129]
	v_add_f32_e32 v194, v92, v194
	v_add_f32_e32 v194, v93, v194
	v_add_f32_e32 v194, v94, v194
	v_add_f32_e32 v194, v95, v194
	v_add_f32_e32 v194, v96, v194
	v_add_f32_e32 v229, v97, v194
	v_mov_b32_e32 v230, v229
	s_waitcnt lgkmcnt(0)
	v_mfma_f32_32x32x16_bf16 v[98:113], v[234:237], v[130:133], v[98:113]
	v_cvt_pk_bf16_f32 v66, v66, v67
	v_cvt_pk_bf16_f32 v67, v68, v69
	v_cvt_pk_bf16_f32 v68, v70, v71
	v_cvt_pk_bf16_f32 v69, v72, v73
	v_cvt_pk_bf16_f32 v70, v74, v75
	v_cvt_pk_bf16_f32 v71, v76, v77
	v_cvt_pk_bf16_f32 v72, v78, v79
	v_cvt_pk_bf16_f32 v73, v80, v81
	v_cvt_pk_bf16_f32 v74, v82, v83
	v_cvt_pk_bf16_f32 v75, v84, v85
	v_cvt_pk_bf16_f32 v76, v86, v87
	v_cvt_pk_bf16_f32 v77, v88, v89
	v_cvt_pk_bf16_f32 v78, v90, v91
	v_cvt_pk_bf16_f32 v79, v92, v93
	v_cvt_pk_bf16_f32 v80, v94, v95
	v_cvt_pk_bf16_f32 v81, v96, v97
	v_permlane32_swap_b32_e32 v229, v230
	v_permlane32_swap_b32_e32 v66, v68
	v_permlane32_swap_b32_e32 v67, v69
	v_permlane32_swap_b32_e32 v70, v72
	v_permlane32_swap_b32_e32 v71, v73
	v_permlane32_swap_b32_e32 v74, v76
	v_permlane32_swap_b32_e32 v75, v77
	v_permlane32_swap_b32_e32 v78, v80
	v_permlane32_swap_b32_e32 v79, v81
	s_add_i32 s81, s81, 2
	s_cmp_ge_u32 s81, s11
	s_cselect_b64 s[64:65], -1, 0
	s_add_i32 m0, s80, s30
	s_nop 0
	global_load_lds_dwordx4 v248, s[26:27]
	s_add_i32 m0, m0, 0x400
	s_nop 0
	global_load_lds_dwordx4 v249, s[26:27]
	s_add_i32 m0, m0, 0xbc00
	s_nop 0
	global_load_lds_dwordx4 v250, s[28:29]
	s_add_i32 m0, m0, 0x400
	s_nop 0
	global_load_lds_dwordx4 v251, s[28:29]
	s_add_u32 s26, s26, 0x90000
	s_addc_u32 s27, s27, 0
	s_add_u32 s28, s28, 0x90000
	s_addc_u32 s29, s29, 0

; __device__ __forceinline__ void finishSM(f32x16& p0, f32x16& p1, float alpha, float& l_reg, bf16x8& pa0, bf16x8& pa1, bf16x8& pa2, bf16x8& pa3) {
; #pragma unroll
;   for (int r = 0; r < 16; ++r) p1[r] = __builtin_amdgcn_exp2f(p1[r]);
;   float ps = 0;
; #pragma unroll
;   for (int r = 0; r < 16; ++r) ps += p0[r];
; #pragma unroll
;   for (int r = 0; r < 16; ++r) ps += p1[r];
;   { auto rr = __builtin_amdgcn_permlane32_swap(__float_as_uint(ps), __float_as_uint(ps), false, false);
;     ps = __uint_as_float(rr[0]) + __uint_as_float(rr[1]); }
;   l_reg = l_reg * alpha + ps;
;     ...
;   PK4(p0, 0, pa0); PK4(p0, 8, pa1); PK4(p1, 0, pa2); PK4(p1, 8, pa3);
;     ...
; }
; template <int ND0, int DOFF>
; __device__ __forceinline__ void qkt(f32x16& p0, f32x16& p1, const char* Ks, const bf16x8* qr, int r32, int hi) {
;   p0 = f32x16{}; p1 = f32x16{};
; #pragma unroll
;   for (int d0 = 0; d0 < ND0; ++d0) { const int cb = ((d0 + DOFF) * 16 + hi * 8) * 2;
;     bf16x8 b0 = *reinterpret_cast<const bf16x8*>(Ks + KSWZ(r32, cb));
;     bf16x8 b1 = *reinterpret_cast<const bf16x8*>(Ks + KSWZ(32 + r32, cb));
;     p0 = __builtin_amdgcn_mfma_f32_32x32x16_bf16(b0, qr[d0], p0, 0, 0, 0);
;     p1 = __builtin_amdgcn_mfma_f32_32x32x16_bf16(b1, qr[d0], p1, 0, 0, 0); }
; }
; __device__ __forceinline__ int v_st(int k, int c) { const int kk = (k & ~0xC) | ((k & 4) << 1) | ((k & 8) >> 1); return ((kk >> 3) * 4 + (c >> 5)) * 512 + ((kk & 7) * 32 + (c & 31)) * 2; }
; __device__ __forceinline__ int v_rd_base(int lane) { return ((lane & 3) << 3) | (((lane >> 2) & 3) << 6) | (((lane >> 4) & 1) << 5) | (((lane >> 5) & 1) << 8); }
; template <int OFF> __device__ __forceinline__ s16x4 tr_read(int vb) {
;   s16x4 r; asm volatile("ds_read_b64_tr_b16 %0, %1 offset:%2" : "=&v"(r) : "v"(vb), "i"(OFF) : "memory"); return r;
; }
; template <int MODE>
; __device__ __forceinline__ void attn_body(const bf16_t* __restrict__ Qb, const bf16_t* __restrict__ Kh, const bf16_t* __restrict__ Vh, int NT, int krel0,
;                                           char* lds, const float* __restrict__ lutg, const AttnEpi& E) {
;     ...
;   for (int j = 1; j + 1 < NT; j += 2) {
;     __syncthreads();
;     SBAR(); qkt<ND0, DOFF>(pB0, pB1, K_lds + oq, qr, r32, hi);
;     finishSM(pA0, pA1, alA, l_reg, pa0, pa1, pa2, pa3); SBAR();
;     SLOAD(SO, (j + 2) * 64); SBAR();
;     pv_d0(o, vb0 + op, pa0, pa1, pa2, pa3); PSM(pB0, pB1, mnB, alB, j);
.LBB0_177:
	v_readfirstlane_b32 s20, v224
	v_readfirstlane_b32 s21, v223
	s_nop 3
	s_add_i32 s22, s20, s77
	s_addk_i32 s22, 0x7f
	s_add_i32 s23, s21, s77
	s_addk_i32 s23, 0x40
	s_add_i32 s24, s22, 64
	s_add_i32 s25, s23, 64
	s_mov_b32 s2, s0
	s_waitcnt vmcnt(0) lgkmcnt(0)
	s_barrier
	s_add_i32 s0, s68, 0
	v_add_u32_e32 v0, s0, v216
	ds_read_b128 v[98:101], v0 offset:49152
	ds_read_b128 v[102:105], v0 offset:57344
	v_add_u32_e32 v0, s0, v217
	ds_read_b128 v[162:165], v0 offset:49152
	ds_read_b128 v[166:169], v0 offset:57344
	v_add_u32_e32 v0, s0, v218
	s_waitcnt lgkmcnt(3)
	v_mfma_f32_32x32x16_bf16 v[114:129], v[98:101], v[142:145], 0
	s_waitcnt lgkmcnt(2)
	v_mfma_f32_32x32x16_bf16 v[98:113], v[102:105], v[142:145], 0
	s_waitcnt lgkmcnt(1)
	v_mfma_f32_32x32x16_bf16 v[114:129], v[162:165], v[138:141], v[114:129]
	s_waitcnt lgkmcnt(0)
	v_mfma_f32_32x32x16_bf16 v[98:113], v[166:169], v[138:141], v[98:113]
	ds_read_b128 v[162:165], v0 offset:49152
	ds_read_b128 v[166:169], v0 offset:57344
	v_add_u32_e32 v0, s0, v219
	s_waitcnt lgkmcnt(1)
	v_mfma_f32_32x32x16_bf16 v[114:129], v[162:165], v[134:137], v[114:129]
	s_waitcnt lgkmcnt(0)
	v_mfma_f32_32x32x16_bf16 v[98:113], v[166:169], v[134:137], v[98:113]
	ds_read_b128 v[162:165], v0 offset:49152
	ds_read_b128 v[166:169], v0 offset:57344
	v_exp_f32_e32 v0, v82
	v_exp_f32_e32 v82, v83
	v_exp_f32_e32 v83, v84
	v_exp_f32_e32 v84, v85
	v_exp_f32_e32 v85, v86
	v_exp_f32_e32 v86, v87
	v_exp_f32_e32 v87, v88
	v_exp_f32_e32 v88, v89
	v_exp_f32_e32 v89, v90
	v_exp_f32_e32 v90, v91
	v_exp_f32_e32 v91, v92
	v_exp_f32_e32 v92, v93
	v_exp_f32_e32 v93, v94
	v_exp_f32_e32 v94, v95
	v_exp_f32_e32 v95, v96
	v_exp_f32_e32 v96, v97
	v_add_f32_e32 v97, v67, v66
	v_add_f32_e32 v97, v68, v97
	v_add_f32_e32 v97, v69, v97
	v_add_f32_e32 v97, v70, v97
	v_add_f32_e32 v97, v71, v97
	v_add_f32_e32 v97, v72, v97
	v_add_f32_e32 v97, v73, v97
	v_add_f32_e32 v97, v74, v97
	v_add_f32_e32 v97, v75, v97
	v_add_f32_e32 v97, v76, v97
	v_add_f32_e32 v97, v77, v97
	v_add_f32_e32 v97, v78, v97
	v_add_f32_e32 v97, v79, v97
	v_add_f32_e32 v97, v80, v97
	v_add_f32_e32 v97, v81, v97
	v_add_f32_e32 v97, v0, v97
	v_add_f32_e32 v97, v82, v97
	v_add_f32_e32 v97, v83, v97
	v_add_f32_e32 v97, v84, v97
	v_add_f32_e32 v97, v85, v97
	v_add_f32_e32 v97, v86, v97
	v_add_f32_e32 v97, v87, v97
	v_add_f32_e32 v97, v88, v97
	v_add_f32_e32 v97, v89, v97
	v_add_f32_e32 v97, v90, v97
	s_waitcnt lgkmcnt(1)
	v_mfma_f32_32x32x16_bf16 v[114:129], v[162:165], v[130:133], v[114:129]
	v_add_f32_e32 v97, v91, v97
	v_add_f32_e32 v97, v92, v97
	v_add_f32_e32 v97, v93, v97
	v_add_f32_e32 v97, v94, v97
	v_add_f32_e32 v97, v95, v97
	v_add_f32_e32 v226, v96, v97
	v_mov_b32_e32 v227, v226
	s_waitcnt lgkmcnt(0)
	v_mfma_f32_32x32x16_bf16 v[98:113], v[166:169], v[130:133], v[98:113]
	v_cvt_pk_bf16_f32 v66, v66, v67
	v_cvt_pk_bf16_f32 v67, v68, v69
	v_cvt_pk_bf16_f32 v68, v70, v71
	v_cvt_pk_bf16_f32 v69, v72, v73
	v_cvt_pk_bf16_f32 v70, v74, v75
	v_cvt_pk_bf16_f32 v71, v76, v77
	v_cvt_pk_bf16_f32 v72, v78, v79
	v_cvt_pk_bf16_f32 v73, v80, v81
	v_cvt_pk_bf16_f32 v74, v0, v82
	v_cvt_pk_bf16_f32 v75, v83, v84
	v_cvt_pk_bf16_f32 v76, v85, v86
	v_cvt_pk_bf16_f32 v77, v87, v88
	v_cvt_pk_bf16_f32 v78, v89, v90
	v_cvt_pk_bf16_f32 v79, v91, v92
	v_cvt_pk_bf16_f32 v80, v93, v94
	v_cvt_pk_bf16_f32 v81, v95, v96
	v_permlane32_swap_b32_e32 v226, v227
	v_permlane32_swap_b32_e32 v66, v68
	v_permlane32_swap_b32_e32 v67, v69
	v_permlane32_swap_b32_e32 v70, v72
	v_permlane32_swap_b32_e32 v71, v73
	v_permlane32_swap_b32_e32 v74, v76
	v_permlane32_swap_b32_e32 v75, v77
	v_permlane32_swap_b32_e32 v78, v80
	v_permlane32_swap_b32_e32 v79, v81
	s_add_i32 m0, s2, s30
	s_nop 0
	global_load_lds_dwordx4 v248, s[26:27]
	s_add_i32 m0, m0, 0x400
	s_nop 0
	global_load_lds_dwordx4 v249, s[26:27]
	s_add_i32 m0, m0, 0xbc00
	s_nop 0
	global_load_lds_dwordx4 v250, s[28:29]
	s_add_i32 m0, m0, 0x400
	s_nop 0
	global_load_lds_dwordx4 v251, s[28:29]
	s_add_u32 s26, s26, 0x90000
	s_addc_u32 s27, s27, 0
	s_add_u32 s28, s28, 0x90000
	s_addc_u32 s29, s29, 0
	v_add_u32_e32 v0, s66, v221
	ds_read_b64_tr_b16 v[82:83], v0 offset:0
	ds_read_b64_tr_b16 v[84:85], v0 offset:0x800
	ds_read_b64_tr_b16 v[86:87], v0 offset:0x1000
	ds_read_b64_tr_b16 v[88:89], v0 offset:0x1800
	ds_read_b64_tr_b16 v[90:91], v0 offset:0x2000
	ds_read_b64_tr_b16 v[92:93], v0 offset:0x2800
	ds_read_b64_tr_b16 v[94:95], v0 offset:0x3000
	ds_read_b64_tr_b16 v[96:97], v0 offset:0x3800
	s_waitcnt lgkmcnt(0)
	s_nop 0
	v_mfma_f32_32x32x16_bf16 v[50:65], v[66:69], v[82:85], v[50:65]
	ds_read_b64_tr_b16 v[82:83], v0 offset:0x200
	ds_read_b64_tr_b16 v[84:85], v0 offset:0xa00
	v_mfma_f32_32x32x16_bf16 v[50:65], v[70:73], v[86:89], v[50:65]
	ds_read_b64_tr_b16 v[86:87], v0 offset:0x1200
	ds_read_b64_tr_b16 v[88:89], v0 offset:0x1a00
	v_mfma_f32_32x32x16_bf16 v[50:65], v[74:77], v[90:93], v[50:65]
	ds_read_b64_tr_b16 v[90:91], v0 offset:0x2200
	ds_read_b64_tr_b16 v[92:93], v0 offset:0x2a00
	v_mfma_f32_32x32x16_bf16 v[50:65], v[78:81], v[94:97], v[50:65]
	ds_read_b64_tr_b16 v[94:95], v0 offset:0x3200
	ds_read_b64_tr_b16 v[96:97], v0 offset:0x3a00
	s_waitcnt lgkmcnt(0)
	v_mfma_f32_32x32x16_bf16 v[34:49], v[66:69], v[82:85], v[34:49]
	ds_read_b64_tr_b16 v[82:83], v0 offset:0x400
	ds_read_b64_tr_b16 v[84:85], v0 offset:0xc00
	v_mfma_f32_32x32x16_bf16 v[34:49], v[70:73], v[86:89], v[34:49]
	ds_read_b64_tr_b16 v[86:87], v0 offset:0x1400
	ds_read_b64_tr_b16 v[88:89], v0 offset:0x1c00
	v_mfma_f32_32x32x16_bf16 v[34:49], v[74:77], v[90:93], v[34:49]
	ds_read_b64_tr_b16 v[90:91], v0 offset:0x2400
	ds_read_b64_tr_b16 v[92:93], v0 offset:0x2c00
	v_mfma_f32_32x32x16_bf16 v[34:49], v[78:81], v[94:97], v[34:49]
	ds_read_b64_tr_b16 v[94:95], v0 offset:0x3400
	ds_read_b64_tr_b16 v[96:97], v0 offset:0x3c00
	s_waitcnt lgkmcnt(0)
	v_mfma_f32_32x32x16_bf16 v[18:33], v[66:69], v[82:85], v[18:33]
	ds_read_b64_tr_b16 v[82:83], v0 offset:0x600
	ds_read_b64_tr_b16 v[84:85], v0 offset:0xe00
	v_mfma_f32_32x32x16_bf16 v[18:33], v[70:73], v[86:89], v[18:33]
	ds_read_b64_tr_b16 v[86:87], v0 offset:0x1600
	ds_read_b64_tr_b16 v[88:89], v0 offset:0x1e00
	v_mfma_f32_32x32x16_bf16 v[18:33], v[74:77], v[90:93], v[18:33]
	ds_read_b64_tr_b16 v[90:91], v0 offset:0x2600
	ds_read_b64_tr_b16 v[92:93], v0 offset:0x2e00
	v_mfma_f32_32x32x16_bf16 v[18:33], v[78:81], v[94:97], v[18:33]
	ds_read_b64_tr_b16 v[94:95], v0 offset:0x3600
	ds_read_b64_tr_b16 v[96:97], v0 offset:0x3e00
	s_waitcnt lgkmcnt(0)
	v_mfma_f32_32x32x16_bf16 v[2:17], v[66:69], v[82:85], v[2:17]
	s_cmp_gt_i32 s95, s22
	s_cselect_b64 s[0:1], -1, 0
	s_cmp_lt_i32 s15, s22
	s_cselect_b64 vcc, -1, 0
	v_mov_b32_e32 v232, s76
	v_mfma_f32_32x32x16_bf16 v[2:17], v[70:73], v[86:89], v[2:17]
	v_mfma_f32_32x32x16_bf16 v[2:17], v[74:77], v[90:93], v[2:17]
	v_mfma_f32_32x32x16_bf16 v[2:17], v[78:81], v[94:97], v[2:17]
	s_and_saveexec_b64 s[58:59], vcc
	s_cbranch_execz .LBB0_181
; template <int MODE>
; __device__ __forceinline__ void partialSM(f32x16& p0, f32x16& p1, float& m_reg, float& mn, float& alpha, int relh, int relw_min, int relw_max, const float* lut) {
;     ...
;     if (nearT) {
; #pragma unroll
;       for (int r = 0; r < 16; ++r) { const int i0 = relh + (r & 3) + 8 * (r >> 2);
;         const int a0 = min(max(i0, -129), 129) + 129, a1 = min(max(i0 + 32, -129), 129) + 129;
;         p0[r] = fmaf(p0[r], C, lut[a0]); p1[r] = fmaf(p1[r], C, lut[a1]); }
	s_cmp_gt_i32 s91, s23
	s_cselect_b64 vcc, -1, 0
	s_mov_b64 s[62:63], -1
	s_and_saveexec_b64 s[60:61], vcc
	s_cbranch_execz .LBB0_180
	v_add_u32_e32 v230, s77, v225
	v_add_u32_e32 v66, 64, v230
	v_add_u32_e32 v68, 0x41, v230
	v_add_u32_e32 v70, 0x42, v230
	v_add_u32_e32 v72, 0x43, v230
	v_med3_i32 v67, v66, s39, v198
	v_med3_i32 v66, v66, s33, v199
	v_med3_i32 v69, v68, s39, v198
	v_med3_i32 v68, v68, s33, v199
	v_med3_i32 v71, v70, s39, v198
	v_med3_i32 v70, v70, s33, v199
	v_med3_i32 v73, v72, s39, v198
	v_med3_i32 v72, v72, s33, v199
	v_lshl_add_u32 v67, v67, 2, s76
	v_lshl_add_u32 v66, v66, 2, s76
	v_lshl_add_u32 v69, v69, 2, s76
	v_lshl_add_u32 v68, v68, 2, s76
	v_lshl_add_u32 v70, v70, 2, s76
	v_lshl_add_u32 v72, v72, 2, s76
	v_lshl_add_u32 v71, v71, 2, s76
	v_lshl_add_u32 v73, v73, 2, s76
	ds_read_b32 v194, v67 offset:516
	ds_read_b32 v66, v66 offset:644
	ds_read_b32 v195, v69 offset:516
	ds_read_b32 v67, v68 offset:644
	ds_read_b32 v232, v71 offset:516
	ds_read_b32 v68, v70 offset:644
	ds_read_b32 v233, v73 offset:516
	ds_read_b32 v69, v72 offset:644
	v_add_u32_e32 v70, 0x48, v230
	v_add_u32_e32 v72, 0x49, v230
	v_add_u32_e32 v74, 0x4a, v230
	v_add_u32_e32 v76, 0x4b, v230
	v_med3_i32 v71, v70, s39, v198
	v_med3_i32 v70, v70, s33, v199
	v_med3_i32 v73, v72, s39, v198
	v_med3_i32 v72, v72, s33, v199
	v_med3_i32 v75, v74, s39, v198
	v_med3_i32 v74, v74, s33, v199
	v_med3_i32 v77, v76, s39, v198
	v_med3_i32 v76, v76, s33, v199
	v_lshl_add_u32 v71, v71, 2, s76
	v_lshl_add_u32 v70, v70, 2, s76
	v_lshl_add_u32 v73, v73, 2, s76
	v_lshl_add_u32 v72, v72, 2, s76
	v_lshl_add_u32 v74, v74, 2, s76
	v_lshl_add_u32 v76, v76, 2, s76
	v_lshl_add_u32 v75, v75, 2, s76
	v_lshl_add_u32 v77, v77, 2, s76
	ds_read_b32 v234, v71 offset:516
	ds_read_b32 v70, v70 offset:644
	ds_read_b32 v235, v73 offset:516
	ds_read_b32 v71, v72 offset:644
	ds_read_b32 v236, v75 offset:516
	ds_read_b32 v72, v74 offset:644
	ds_read_b32 v237, v77 offset:516
	ds_read_b32 v73, v76 offset:644
	v_add_u32_e32 v74, 0x50, v230
	v_add_u32_e32 v76, 0x51, v230
	v_add_u32_e32 v78, 0x52, v230
	v_add_u32_e32 v80, 0x53, v230
	v_med3_i32 v75, v74, s39, v198
	v_med3_i32 v74, v74, s33, v199
	v_med3_i32 v77, v76, s39, v198
	v_med3_i32 v76, v76, s33, v199
	v_med3_i32 v79, v78, s39, v198
	v_med3_i32 v78, v78, s33, v199
	v_med3_i32 v81, v80, s39, v198
	v_med3_i32 v80, v80, s33, v199
	v_lshl_add_u32 v75, v75, 2, s76
	v_lshl_add_u32 v74, v74, 2, s76
	v_lshl_add_u32 v77, v77, 2, s76
	v_lshl_add_u32 v76, v76, 2, s76
	v_lshl_add_u32 v78, v78, 2, s76
	v_lshl_add_u32 v80, v80, 2, s76
	v_lshl_add_u32 v79, v79, 2, s76
	v_lshl_add_u32 v81, v81, 2, s76
	ds_read_b32 v238, v75 offset:516
	ds_read_b32 v74, v74 offset:644
	ds_read_b32 v239, v77 offset:516
	ds_read_b32 v75, v76 offset:644
	ds_read_b32 v240, v79 offset:516
	ds_read_b32 v76, v78 offset:644
	ds_read_b32 v241, v81 offset:516
	ds_read_b32 v77, v80 offset:644
	v_add_u32_e32 v78, 0x58, v230
	v_add_u32_e32 v80, 0x59, v230
	v_add_u32_e32 v82, 0x5a, v230
	v_med3_i32 v79, v78, s39, v198
	v_med3_i32 v78, v78, s33, v199
	v_med3_i32 v81, v80, s39, v198
	v_med3_i32 v80, v80, s33, v199
	v_med3_i32 v83, v82, s39, v198
	v_med3_i32 v82, v82, s33, v199
	v_add_u32_e32 v84, 0x5b, v230
	s_waitcnt lgkmcnt(14)
	v_fmac_f32_e32 v194, 0x3e38aa3b, v114
	v_fmac_f32_e32 v195, 0x3e38aa3b, v115
	v_lshl_add_u32 v79, v79, 2, s76
	v_lshl_add_u32 v78, v78, 2, s76
	v_lshl_add_u32 v81, v81, 2, s76
	v_lshl_add_u32 v80, v80, 2, s76
	v_lshl_add_u32 v82, v82, 2, s76
	v_med3_i32 v85, v84, s39, v198
	v_med3_i32 v84, v84, s33, v199
	v_fmac_f32_e32 v232, 0x3e38aa3b, v116
	v_fmac_f32_e32 v233, 0x3e38aa3b, v117
	v_lshl_add_u32 v83, v83, 2, s76
	v_lshl_add_u32 v85, v85, 2, s76
	v_lshl_add_u32 v84, v84, 2, s76
	ds_read_b32 v242, v79 offset:516
	ds_read_b32 v78, v78 offset:644
	ds_read_b32 v243, v81 offset:516
	ds_read_b32 v79, v80 offset:644
	ds_read_b32 v244, v83 offset:516
	ds_read_b32 v80, v82 offset:644
	ds_read_b32 v245, v85 offset:516
	ds_read_b32 v81, v84 offset:644
	v_max_f32_e32 v82, v194, v195
	v_fmac_f32_e32 v234, 0x3e38aa3b, v118
	s_waitcnt lgkmcnt(14)
; template <int MODE>
; __device__ __forceinline__ void partialSM(f32x16& p0, f32x16& p1, float& m_reg, float& mn, float& alpha, int relh, int relw_min, int relw_max, const float* lut) {
;     ...
;     float pmax = p0[0];
; #pragma unroll
;     for (int r = 1; r < 16; ++r) pmax = fmaxf(pmax, p0[r]);
; #pragma unroll
;     for (int r = 0; r < 16; ++r) pmax = fmaxf(pmax, p1[r]);
;     { auto rr = __builtin_amdgcn_permlane32_swap(__float_as_uint(pmax), __float_as_uint(pmax), false, false);
;       pmax = fmaxf(__uint_as_float(rr[0]), __uint_as_float(rr[1])); }
;     if (__builtin_expect(__all(pmax - m_reg <= THR2), 1)) { mn = m_reg; alpha = 1.f; }
;     else { mn = fmaxf(m_reg, pmax); alpha = __builtin_amdgcn_exp2f(m_reg - mn); m_reg = mn; }
; #pragma unroll
;     for (int r = 0; r < 16; ++r) p0[r] = __builtin_amdgcn_exp2f(p0[r] - mn);
; #pragma unroll
;     for (int r = 0; r < 16; ++r) p1[r] = p1[r] - mn;
	v_fmac_f32_e32 v235, 0x3e38aa3b, v119
	v_max3_f32 v82, v82, v232, v233
	v_fmac_f32_e32 v236, 0x3e38aa3b, v120
	v_fmac_f32_e32 v237, 0x3e38aa3b, v121
	v_max3_f32 v82, v82, v234, v235
	v_fmac_f32_e32 v238, 0x3e38aa3b, v122
	s_waitcnt lgkmcnt(13)
	v_fmac_f32_e32 v239, 0x3e38aa3b, v123
	v_max3_f32 v82, v82, v236, v237
	s_waitcnt lgkmcnt(11)
	v_fmac_f32_e32 v240, 0x3e38aa3b, v124
	s_waitcnt lgkmcnt(9)
	v_fmac_f32_e32 v241, 0x3e38aa3b, v125
	v_max3_f32 v82, v82, v238, v239
	s_waitcnt lgkmcnt(7)
	v_fmac_f32_e32 v242, 0x3e38aa3b, v126
	s_waitcnt lgkmcnt(5)
	v_fmac_f32_e32 v243, 0x3e38aa3b, v127
	v_max3_f32 v82, v82, v240, v241
	s_waitcnt lgkmcnt(3)
	v_fmac_f32_e32 v244, 0x3e38aa3b, v128
	s_waitcnt lgkmcnt(1)
	v_fmac_f32_e32 v245, 0x3e38aa3b, v129
	v_max3_f32 v82, v82, v242, v243
	v_max3_f32 v84, v82, v244, v245
	v_pk_fma_f32 v[82:83], v[98:99], s[48:49], v[66:67] op_sel_hi:[1,0,1]
	v_pk_fma_f32 v[86:87], v[102:103], s[48:49], v[70:71] op_sel_hi:[1,0,1]
	v_max3_f32 v66, v84, v82, v83
	v_pk_fma_f32 v[84:85], v[100:101], s[48:49], v[68:69] op_sel_hi:[1,0,1]
	v_pk_fma_f32 v[88:89], v[104:105], s[48:49], v[72:73] op_sel_hi:[1,0,1]
	v_max3_f32 v66, v66, v84, v85
	v_max3_f32 v66, v66, v86, v87
	v_max3_f32 v66, v66, v88, v89
	v_pk_fma_f32 v[90:91], v[106:107], s[48:49], v[74:75] op_sel_hi:[1,0,1]
	v_pk_fma_f32 v[92:93], v[108:109], s[48:49], v[76:77] op_sel_hi:[1,0,1]
	v_max3_f32 v66, v66, v90, v91
	v_max3_f32 v66, v66, v92, v93
	v_pk_fma_f32 v[94:95], v[110:111], s[48:49], v[78:79] op_sel_hi:[1,0,1]
	s_waitcnt lgkmcnt(0)
	v_pk_fma_f32 v[96:97], v[112:113], s[48:49], v[80:81] op_sel_hi:[1,0,1]
	v_max3_f32 v66, v66, v94, v95
	v_max3_f32 v66, v66, v96, v97
	v_mov_b32_e32 v67, v66
	s_nop 1
	v_permlane32_swap_b32_e32 v66, v67
	v_max_f32_e32 v66, v66, v67
	v_sub_f32_e32 v67, v66, v222
	v_cmp_ge_f32_e32 vcc, s94, v67
	v_max_f32_e32 v66, v222, v66
	v_sub_f32_e32 v67, v222, v66
	v_exp_f32_e32 v67, v67
	s_cmp_eq_u64 vcc, exec
	s_cselect_b64 vcc, -1, 0
	v_cndmask_b32_e32 v231, v66, v222, vcc
	v_cndmask_b32_e64 v229, v67, 1.0, vcc
	v_sub_f32_e32 v66, v194, v231
	v_sub_f32_e32 v67, v195, v231
	v_sub_f32_e32 v68, v232, v231
	v_sub_f32_e32 v69, v233, v231
	v_sub_f32_e32 v70, v234, v231
	v_sub_f32_e32 v71, v235, v231
	v_sub_f32_e32 v72, v236, v231
	v_sub_f32_e32 v73, v237, v231
	v_sub_f32_e32 v74, v238, v231
	v_sub_f32_e32 v75, v239, v231
	v_sub_f32_e32 v76, v240, v231
	v_sub_f32_e32 v77, v241, v231
	v_sub_f32_e32 v78, v242, v231
	v_sub_f32_e32 v79, v243, v231
	v_sub_f32_e32 v80, v244, v231
	v_sub_f32_e32 v81, v245, v231
	v_exp_f32_e32 v66, v66
	v_exp_f32_e32 v67, v67
	v_exp_f32_e32 v68, v68
	v_exp_f32_e32 v69, v69
	v_exp_f32_e32 v70, v70
	v_exp_f32_e32 v71, v71
	v_exp_f32_e32 v72, v72
	v_exp_f32_e32 v73, v73
	v_exp_f32_e32 v74, v74
	v_exp_f32_e32 v75, v75
	v_exp_f32_e32 v76, v76
	v_exp_f32_e32 v77, v77
	v_exp_f32_e32 v78, v78
	v_exp_f32_e32 v79, v79
	v_exp_f32_e32 v80, v80
	v_exp_f32_e32 v81, v81
	v_sub_f32_e32 v97, v97, v231
	v_sub_f32_e32 v96, v96, v231
	v_sub_f32_e32 v95, v95, v231
	v_sub_f32_e32 v94, v94, v231
	v_sub_f32_e32 v93, v93, v231
	v_sub_f32_e32 v92, v92, v231
	v_sub_f32_e32 v91, v91, v231
	v_sub_f32_e32 v90, v90, v231
	v_sub_f32_e32 v89, v89, v231
	v_sub_f32_e32 v88, v88, v231
	v_sub_f32_e32 v87, v87, v231
	v_sub_f32_e32 v86, v86, v231
	v_sub_f32_e32 v85, v85, v231
	v_sub_f32_e32 v84, v84, v231
	v_sub_f32_e32 v83, v83, v231
	v_sub_f32_e32 v82, v82, v231
	s_xor_b64 s[62:63], exec, -1

; #define SBAR() __builtin_amdgcn_sched_barrier(0)
; #define SLOAD(i, k0) do { sr_[i].vs0 = *reinterpret_cast<const bf16x8*>(&Vh[(size_t)((k0) + sr) * LDQK + sc]); sr_[i].vs1 = *reinterpret_cast<const bf16x8*>(&Vh[(size_t)((k0) + 32 + sr) * LDQK + sc]); \
;     sr_[i].ks0 = *reinterpret_cast<const bf16x8*>(&Kh[(size_t)((k0) + sr) * LDQK + sc]); sr_[i].ks1 = *reinterpret_cast<const bf16x8*>(&Kh[(size_t)((k0) + 32 + sr) * LDQK + sc]); } while (0)
; __device__ __forceinline__ void finishSM(f32x16& p0, f32x16& p1, float alpha, float& l_reg, bf16x8& pa0, bf16x8& pa1, bf16x8& pa2, bf16x8& pa3) {
; #pragma unroll
;   for (int r = 0; r < 16; ++r) p1[r] = __builtin_amdgcn_exp2f(p1[r]);
;   float ps = 0;
; #pragma unroll
;   for (int r = 0; r < 16; ++r) ps += p0[r];
; #pragma unroll
;   for (int r = 0; r < 16; ++r) ps += p1[r];
;   { auto rr = __builtin_amdgcn_permlane32_swap(__float_as_uint(ps), __float_as_uint(ps), false, false);
;     ps = __uint_as_float(rr[0]) + __uint_as_float(rr[1]); }
;   l_reg = l_reg * alpha + ps;
;     ...
;   PK4(p0, 0, pa0); PK4(p0, 8, pa1); PK4(p1, 0, pa2); PK4(p1, 8, pa3);
;     ...
; }
; template <int ND0, int DOFF>
; __device__ __forceinline__ void qkt(f32x16& p0, f32x16& p1, const char* Ks, const bf16x8* qr, int r32, int hi) {
;   p0 = f32x16{}; p1 = f32x16{};
; #pragma unroll
;   for (int d0 = 0; d0 < ND0; ++d0) { const int cb = ((d0 + DOFF) * 16 + hi * 8) * 2;
;     bf16x8 b0 = *reinterpret_cast<const bf16x8*>(Ks + KSWZ(r32, cb));
;     bf16x8 b1 = *reinterpret_cast<const bf16x8*>(Ks + KSWZ(32 + r32, cb));
;     p0 = __builtin_amdgcn_mfma_f32_32x32x16_bf16(b0, qr[d0], p0, 0, 0, 0);
;     p1 = __builtin_amdgcn_mfma_f32_32x32x16_bf16(b1, qr[d0], p1, 0, 0, 0); }
; }
; template <int MODE>
; __device__ __forceinline__ void attn_body(const bf16_t* __restrict__ Qb, const bf16_t* __restrict__ Kh, const bf16_t* __restrict__ Vh, int NT, int krel0,
;                                           char* lds, const float* __restrict__ lutg, const AttnEpi& E) {
;     ...
;     __syncthreads();
;     SBAR(); qkt<ND0, DOFF>(pA0, pA1, K_lds + oq, qr, r32, hi);
;     finishSM(pB0, pB1, alB, l_reg, pa0, pa1, pa2, pa3); SBAR();
;     if (j + 3 < NT) SLOAD(SE, (j + 3) * 64); SBAR();
.LBB0_187:
	s_waitcnt vmcnt(0) lgkmcnt(0)
	s_barrier
	v_add_u32_e32 v102, s58, v216
	ds_read_b128 v[98:101], v102 offset:49152
	ds_read_b128 v[102:105], v102 offset:57344
	v_add_u32_e32 v194, s58, v217
	ds_read_b128 v[232:235], v194 offset:49152
	ds_read_b128 v[236:239], v194 offset:57344
	v_add_u32_e32 v194, s58, v218
	s_waitcnt lgkmcnt(3)
	v_mfma_f32_32x32x16_bf16 v[114:129], v[98:101], v[142:145], 0
	v_exp_f32_e32 v82, v82
	v_exp_f32_e32 v83, v83
	v_exp_f32_e32 v84, v84
	v_exp_f32_e32 v85, v85
	v_exp_f32_e32 v86, v86
	v_exp_f32_e32 v87, v87
	v_exp_f32_e32 v88, v88
	s_waitcnt lgkmcnt(2)
	v_mfma_f32_32x32x16_bf16 v[98:113], v[102:105], v[142:145], 0
	v_exp_f32_e32 v89, v89
	v_exp_f32_e32 v90, v90
	v_exp_f32_e32 v91, v91
	v_exp_f32_e32 v92, v92
	v_exp_f32_e32 v93, v93
	v_exp_f32_e32 v94, v94
	v_exp_f32_e32 v95, v95
	s_waitcnt lgkmcnt(1)
	v_mfma_f32_32x32x16_bf16 v[114:129], v[232:235], v[138:141], v[114:129]
	v_exp_f32_e32 v96, v96
	v_exp_f32_e32 v97, v97
	s_waitcnt lgkmcnt(0)
	v_mfma_f32_32x32x16_bf16 v[98:113], v[236:239], v[138:141], v[98:113]
	ds_read_b128 v[232:235], v194 offset:49152
	ds_read_b128 v[236:239], v194 offset:57344
	v_add_u32_e32 v194, s58, v219
	s_waitcnt lgkmcnt(1)
	v_mfma_f32_32x32x16_bf16 v[114:129], v[232:235], v[134:137], v[114:129]
	s_waitcnt lgkmcnt(0)
	v_mfma_f32_32x32x16_bf16 v[98:113], v[236:239], v[134:137], v[98:113]
	ds_read_b128 v[232:235], v194 offset:49152
	ds_read_b128 v[236:239], v194 offset:57344
	v_add_f32_e32 v194, v67, v66
	v_add_f32_e32 v194, v68, v194
	v_add_f32_e32 v194, v69, v194
	v_add_f32_e32 v194, v70, v194
	v_add_f32_e32 v194, v71, v194
	v_add_f32_e32 v194, v72, v194
	v_add_f32_e32 v194, v73, v194
	v_add_f32_e32 v194, v74, v194
	v_add_f32_e32 v194, v75, v194
	v_add_f32_e32 v194, v76, v194
	v_add_f32_e32 v194, v77, v194
	v_add_f32_e32 v194, v78, v194
	v_add_f32_e32 v194, v79, v194
	v_add_f32_e32 v194, v80, v194
	v_add_f32_e32 v194, v81, v194
	v_add_f32_e32 v194, v82, v194
	v_add_f32_e32 v194, v83, v194
	v_add_f32_e32 v194, v84, v194
	v_add_f32_e32 v194, v85, v194
	v_add_f32_e32 v194, v86, v194
	v_add_f32_e32 v194, v87, v194
	v_add_f32_e32 v194, v88, v194
	v_add_f32_e32 v194, v89, v194
	v_add_f32_e32 v194, v90, v194
	v_add_f32_e32 v194, v91, v194
	s_waitcnt lgkmcnt(1)
	v_mfma_f32_32x32x16_bf16 v[114:129], v[232:235], v[130:133], v[114:129]
	v_add_f32_e32 v194, v92, v194
	v_add_f32_e32 v194, v93, v194
	v_add_f32_e32 v194, v94, v194
	v_add_f32_e32 v194, v95, v194
	v_add_f32_e32 v194, v96, v194
	v_add_f32_e32 v232, v97, v194
	v_mov_b32_e32 v233, v232
	s_waitcnt lgkmcnt(0)
	v_mfma_f32_32x32x16_bf16 v[98:113], v[236:239], v[130:133], v[98:113]
	v_cvt_pk_bf16_f32 v66, v66, v67
	v_cvt_pk_bf16_f32 v67, v68, v69
	v_cvt_pk_bf16_f32 v68, v70, v71
	v_cvt_pk_bf16_f32 v69, v72, v73
	v_cvt_pk_bf16_f32 v70, v74, v75
	v_cvt_pk_bf16_f32 v71, v76, v77
	v_cvt_pk_bf16_f32 v72, v78, v79
	v_cvt_pk_bf16_f32 v73, v80, v81
	v_cvt_pk_bf16_f32 v74, v82, v83
	v_cvt_pk_bf16_f32 v75, v84, v85
	v_cvt_pk_bf16_f32 v76, v86, v87
	v_cvt_pk_bf16_f32 v77, v88, v89
	v_cvt_pk_bf16_f32 v78, v90, v91
	v_cvt_pk_bf16_f32 v79, v92, v93
	v_cvt_pk_bf16_f32 v80, v94, v95
	v_cvt_pk_bf16_f32 v81, v96, v97
	v_permlane32_swap_b32_e32 v232, v233
	v_permlane32_swap_b32_e32 v66, v68
	v_permlane32_swap_b32_e32 v67, v69
	v_permlane32_swap_b32_e32 v70, v72
	v_permlane32_swap_b32_e32 v71, v73
	v_permlane32_swap_b32_e32 v74, v76
	v_permlane32_swap_b32_e32 v75, v77
	v_permlane32_swap_b32_e32 v78, v80
	v_permlane32_swap_b32_e32 v79, v81
	s_add_i32 s67, s67, 2
	s_cmp_ge_u32 s67, s11
	s_cselect_b64 s[0:1], -1, 0
	s_add_i32 m0, s66, s30
	s_nop 0
	global_load_lds_dwordx4 v248, s[26:27]
	s_add_i32 m0, m0, 0x400
	s_nop 0
	global_load_lds_dwordx4 v249, s[26:27]
	s_add_i32 m0, m0, 0xbc00
	s_nop 0
	global_load_lds_dwordx4 v250, s[28:29]
	s_add_i32 m0, m0, 0x400
	s_nop 0
	global_load_lds_dwordx4 v251, s[28:29]
	s_add_u32 s26, s26, 0x90000
	s_addc_u32 s27, s27, 0
	s_add_u32 s28, s28, 0x90000
	s_addc_u32 s29, s29, 0
